# attention: K/V prefetch loads via saddr + 32-bit offsets (fewer address VALU), 3 v_mov folded into early v_exp
# speedup vs baseline: 1.0019x; 1.0019x over previous
; #define MFMA(a, b, c) __builtin_amdgcn_mfma_f32_16x16x32_bf16(a, b, c, 0, 0, 0)
; DEV float shfl_l(float v, int srclane) { return __int_as_float(__builtin_amdgcn_ds_bpermute(srclane << 2, __float_as_int(v))); }
; DEV float ex2(float x) { return __builtin_amdgcn_exp2f(x); }
; DEV void attn_item(const Params& p, int layer, int h, int qb, float lam, bf16_t* lds) {
;     ...
;       float ps = 0.f;
; #pragma unroll
;       for (int j = 0; j < 8; j++)
; #pragma unroll
;         for (int r = 0; r < 4; r++) { const float pv = ex2(s[i][j][r] - mnew); s[i][j][r] = pv; ps += pv; }
;       if (i == 0) { mrun0 = mnew; lrun0 = lrun0 * al[0] + ps; } else { mrun1 = mnew; lrun1 = lrun1 * al[1] + ps; }
;     }
;     if (__builtin_amdgcn_ballot_w64(al[0] != 1.f || al[1] != 1.f) != 0ull) {
; #pragma unroll
;       for (int i = 0; i < 2; i++) {
;         float ao[4];
; #pragma unroll
;         for (int r = 0; r < 4; r++) ao[r] = shfl_l(al[i], lg * 4 + r);
; #pragma unroll
;         for (int je = 0; je < 8; je++)
; #pragma unroll
;           for (int r = 0; r < 4; r++) o[i][je][r] *= ao[r];
;       }
;     }
; #pragma unroll
;     for (int ks = 0; ks < 4; ks++) {
;       union { u32x4 u; bf16x8 v; } pf0, pf1;
;       pf0.u[0] = pack2(s[0][2 * ks][0], s[0][2 * ks][1]);
;       pf0.u[1] = pack2(s[0][2 * ks][2], s[0][2 * ks][3]);
;       pf0.u[2] = pack2(s[0][2 * ks + 1][0], s[0][2 * ks + 1][1]);
;       pf0.u[3] = pack2(s[0][2 * ks + 1][2], s[0][2 * ks + 1][3]);
;       pf1.u[0] = pack2(s[1][2 * ks][0], s[1][2 * ks][1]);
;       pf1.u[1] = pack2(s[1][2 * ks][2], s[1][2 * ks][3]);
;       pf1.u[2] = pack2(s[1][2 * ks + 1][0], s[1][2 * ks + 1][1]);
;       pf1.u[3] = pack2(s[1][2 * ks + 1][2], s[1][2 * ks + 1][3]);
; #pragma unroll
;       for (int je = 0; je < 8; je++) {
;         const bf16_t* vp = vq + je * 16 * PS + ks * 32;
;         union { uint2 u[2]; bf16x8 v; } vf;
;         vf.u[0] = *(const uint2*)vp;
;         vf.u[1] = *(const uint2*)(vp + 16);
;         o[0][je] = MFMA(pf0.v, vf.v, o[0][je]);
;         o[1][je] = MFMA(pf1.v, vf.v, o[1][je]);
;       }
;     }
.LBB0_707:
	v_exp_f32_e32 v199, v176
	v_exp_f32_e32 v203, v177
	v_exp_f32_e32 v195, v178
	v_exp_f32_e32 v197, v179
	v_exp_f32_e32 v201, v172
	v_exp_f32_e32 v177, v173
	v_exp_f32_e32 v179, v174
	v_exp_f32_e32 v173, v175
	v_exp_f32_e32 v175, v160
	v_exp_f32_e32 v161, v161
	v_exp_f32_e32 v198, v168
	v_exp_f32_e32 v202, v169
	v_exp_f32_e32 v194, v170
	v_exp_f32_e32 v196, v171
	v_exp_f32_e32 v200, v164
	v_exp_f32_e32 v176, v165
	v_exp_f32_e32 v178, v166
	v_exp_f32_e32 v172, v167
	v_lshl_add_u32 v0, s67, 1, v232
	v_cvt_pk_bf16_f32 v236, v199, v203
	v_cvt_pk_bf16_f32 v237, v195, v197
	v_cvt_pk_bf16_f32 v238, v201, v177
	v_cvt_pk_bf16_f32 v239, v179, v173
	ds_read_b128 v[164:167], v0
	v_cvt_pk_bf16_f32 v240, v198, v202
	v_cvt_pk_bf16_f32 v241, v194, v196
	v_cvt_pk_bf16_f32 v242, v200, v176
	v_cvt_pk_bf16_f32 v243, v178, v172
	ds_read_b128 v[244:247], v0 offset:8704
	ds_read_b128 v[248:251], v0 offset:13056
	s_waitcnt lgkmcnt(2)
	v_mfma_f32_16x16x32_bf16 v[100:103], v[236:239], v[164:167], v[100:103]
	v_exp_f32_e32 v174, v152
	v_mfma_f32_16x16x32_bf16 v[80:83], v[240:243], v[164:167], v[80:83]
	v_exp_f32_e32 v165, v162
	v_exp_f32_e32 v163, v163
	v_exp_f32_e32 v160, v153
	ds_read_b128 v[168:171], v0 offset:4352
	s_waitcnt lgkmcnt(2)
	v_mfma_f32_16x16x32_bf16 v[112:115], v[236:239], v[244:247], v[112:115]
	v_exp_f32_e32 v164, v154
	v_mfma_f32_16x16x32_bf16 v[72:75], v[240:243], v[244:247], v[72:75]
	ds_read_b128 v[244:247], v0 offset:17408
	v_exp_f32_e32 v162, v155
	ds_read_b128 v[152:155], v0 offset:26112
	s_waitcnt lgkmcnt(3)
	v_mfma_f32_16x16x32_bf16 v[92:95], v[236:239], v[248:251], v[92:95]
	v_exp_f32_e32 v167, v156
	v_mfma_f32_16x16x32_bf16 v[68:71], v[240:243], v[248:251], v[68:71]
	ds_read_b128 v[248:251], v0 offset:21760
	v_exp_f32_e32 v157, v157
	s_waitcnt lgkmcnt(3)
	v_mfma_f32_16x16x32_bf16 v[96:99], v[236:239], v[168:171], v[96:99]
	v_exp_f32_e32 v166, v148
	v_mfma_f32_16x16x32_bf16 v[76:79], v[240:243], v[168:171], v[76:79]
	v_exp_f32_e32 v169, v158
	v_exp_f32_e32 v159, v159
	s_waitcnt lgkmcnt(2)
	v_mfma_f32_16x16x32_bf16 v[108:111], v[236:239], v[244:247], v[108:111]
	v_exp_f32_e32 v168, v150
	ds_read_b128 v[208:211], v0 offset:17472
	v_mfma_f32_16x16x32_bf16 v[64:67], v[240:243], v[244:247], v[64:67]
	v_exp_f32_e32 v171, v128
	s_waitcnt lgkmcnt(1)
	v_mfma_f32_16x16x32_bf16 v[244:247], v[240:243], v[248:251], v[60:63]
	v_exp_f32_e32 v221, v129
	v_exp_f32_e32 v156, v149
	v_mfma_f32_16x16x32_bf16 v[104:107], v[236:239], v[152:155], v[104:107]
	ds_read_b128 v[60:63], v0 offset:30464
	v_exp_f32_e32 v170, v120
	v_mfma_f32_16x16x32_bf16 v[152:155], v[240:243], v[152:155], v[56:59]
	v_exp_f32_e32 v220, v121
	v_exp_f32_e32 v158, v151
	v_mfma_f32_16x16x32_bf16 v[88:91], v[236:239], v[248:251], v[88:91]
	ds_read_b128 v[56:59], v0 offset:64
	v_cvt_pk_bf16_f32 v248, v174, v160
	v_cvt_pk_bf16_f32 v249, v164, v162
	s_waitcnt lgkmcnt(1)
	v_mfma_f32_16x16x32_bf16 v[148:151], v[236:239], v[60:63], v[84:87]
	v_cvt_pk_bf16_f32 v236, v175, v161
	v_cvt_pk_bf16_f32 v237, v165, v163
	v_cvt_pk_bf16_f32 v238, v167, v157
	v_cvt_pk_bf16_f32 v239, v169, v159
	v_cvt_pk_bf16_f32 v250, v166, v156
	v_cvt_pk_bf16_f32 v251, v168, v158
	s_waitcnt lgkmcnt(0)
	v_mfma_f32_16x16x32_bf16 v[100:103], v[236:239], v[56:59], v[100:103]
	ds_read_b128 v[84:87], v0 offset:8768
	v_mfma_f32_16x16x32_bf16 v[80:83], v[248:251], v[56:59], v[80:83]
	ds_read_b128 v[56:59], v0 offset:4416
	v_mfma_f32_16x16x32_bf16 v[240:243], v[240:243], v[60:63], v[52:55]
	v_exp_f32_e32 v60, v133
	s_nop 1
	v_exp_f32_e32 v53, v144
	v_exp_f32_e32 v55, v145
	s_waitcnt lgkmcnt(0)
	v_mfma_f32_16x16x32_bf16 v[96:99], v[236:239], v[56:59], v[96:99]
	v_exp_f32_e32 v54, v137
	v_mfma_f32_16x16x32_bf16 v[76:79], v[248:251], v[56:59], v[76:79]
	v_exp_f32_e32 v57, v146
	v_exp_f32_e32 v63, v147
	ds_read_b128 v[144:147], v0 offset:13120
	v_exp_f32_e32 v59, v140
	v_exp_f32_e32 v61, v141
	v_mfma_f32_16x16x32_bf16 v[112:115], v[236:239], v[84:87], v[112:115]
	v_exp_f32_e32 v56, v138
	v_exp_f32_e32 v62, v139
	v_mfma_f32_16x16x32_bf16 v[72:75], v[248:251], v[84:87], v[72:75]
	v_exp_f32_e32 v85, v142
	v_exp_f32_e32 v87, v143
	s_waitcnt lgkmcnt(0)
	v_mfma_f32_16x16x32_bf16 v[92:95], v[236:239], v[144:147], v[92:95]
	v_exp_f32_e32 v52, v136
	ds_read_b128 v[140:143], v0 offset:21824
	ds_read_b128 v[136:139], v0 offset:26176
	v_mfma_f32_16x16x32_bf16 v[68:71], v[248:251], v[144:147], v[68:71]
	ds_read_b128 v[144:147], v0 offset:30528
	v_exp_f32_e32 v58, v132
	v_exp_f32_e32 v84, v134
	v_exp_f32_e32 v86, v135
	v_mfma_f32_16x16x32_bf16 v[108:111], v[236:239], v[208:211], v[108:111]
	v_mfma_f32_16x16x32_bf16 v[64:67], v[248:251], v[208:211], v[64:67]
	v_cvt_pk_bf16_f32 v208, v52, v54
	v_cvt_pk_bf16_f32 v209, v56, v62
	v_cvt_pk_bf16_f32 v210, v58, v60
	s_waitcnt lgkmcnt(2)
	v_mfma_f32_16x16x32_bf16 v[88:91], v[236:239], v[140:143], v[88:91]
	v_cvt_pk_bf16_f32 v211, v84, v86
	s_waitcnt lgkmcnt(1)
	v_mfma_f32_16x16x32_bf16 v[104:107], v[236:239], v[136:139], v[104:107]
	s_waitcnt lgkmcnt(0)
	v_mfma_f32_16x16x32_bf16 v[132:135], v[236:239], v[144:147], v[148:151]
	ds_read_b128 v[236:239], v0 offset:8832
	s_nop 1
	v_cvt_pk_bf16_f32 v148, v53, v55
	v_cvt_pk_bf16_f32 v149, v57, v63
	v_cvt_pk_bf16_f32 v150, v59, v61
	v_cvt_pk_bf16_f32 v151, v85, v87
	v_mfma_f32_16x16x32_bf16 v[144:147], v[248:251], v[144:147], v[240:243]
	s_nop 2
	v_exp_f32_e32 v241, v130
	v_exp_f32_e32 v243, v131
	ds_read_b128 v[128:131], v0 offset:13184
	s_waitcnt lgkmcnt(1)
; #define MFMA(a, b, c) __builtin_amdgcn_mfma_f32_16x16x32_bf16(a, b, c, 0, 0, 0)
; DEV float shfl_l(float v, int srclane) { return __int_as_float(__builtin_amdgcn_ds_bpermute(srclane << 2, __float_as_int(v))); }
; DEV float ex2(float x) { return __builtin_amdgcn_exp2f(x); }
; DEV void attn_item(const Params& p, int layer, int h, int qb, float lam, bf16_t* lds) {
;     ...
;       float ps = 0.f;
; #pragma unroll
;       for (int j = 0; j < 8; j++)
; #pragma unroll
;         for (int r = 0; r < 4; r++) { const float pv = ex2(s[i][j][r] - mnew); s[i][j][r] = pv; ps += pv; }
;       if (i == 0) { mrun0 = mnew; lrun0 = lrun0 * al[0] + ps; } else { mrun1 = mnew; lrun1 = lrun1 * al[1] + ps; }
;     }
;     if (__builtin_amdgcn_ballot_w64(al[0] != 1.f || al[1] != 1.f) != 0ull) {
; #pragma unroll
;       for (int i = 0; i < 2; i++) {
;         float ao[4];
; #pragma unroll
;         for (int r = 0; r < 4; r++) ao[r] = shfl_l(al[i], lg * 4 + r);
; #pragma unroll
;         for (int je = 0; je < 8; je++)
; #pragma unroll
;           for (int r = 0; r < 4; r++) o[i][je][r] *= ao[r];
;       }
;     }
; #pragma unroll
;     for (int ks = 0; ks < 4; ks++) {
;       union { u32x4 u; bf16x8 v; } pf0, pf1;
;       pf0.u[0] = pack2(s[0][2 * ks][0], s[0][2 * ks][1]);
;       pf0.u[1] = pack2(s[0][2 * ks][2], s[0][2 * ks][3]);
;       pf0.u[2] = pack2(s[0][2 * ks + 1][0], s[0][2 * ks + 1][1]);
;       pf0.u[3] = pack2(s[0][2 * ks + 1][2], s[0][2 * ks + 1][3]);
;       pf1.u[0] = pack2(s[1][2 * ks][0], s[1][2 * ks][1]);
;       pf1.u[1] = pack2(s[1][2 * ks][2], s[1][2 * ks][3]);
;       pf1.u[2] = pack2(s[1][2 * ks + 1][0], s[1][2 * ks + 1][1]);
;       pf1.u[3] = pack2(s[1][2 * ks + 1][2], s[1][2 * ks + 1][3]);
; #pragma unroll
;       for (int je = 0; je < 8; je++) {
;         const bf16_t* vp = vq + je * 16 * PS + ks * 32;
;         union { uint2 u[2]; bf16x8 v; } vf;
;         vf.u[0] = *(const uint2*)vp;
;         vf.u[1] = *(const uint2*)(vp + 16);
;         o[0][je] = MFMA(pf0.v, vf.v, o[0][je]);
;         o[1][je] = MFMA(pf1.v, vf.v, o[1][je]);
;       }
;     }
;     __builtin_amdgcn_sched_barrier(0);
;     __syncthreads();
;   }
	v_mfma_f32_16x16x32_bf16 v[112:115], v[148:151], v[236:239], v[112:115]
	v_exp_f32_e32 v240, v122
	v_exp_f32_e32 v242, v123
	v_mfma_f32_16x16x32_bf16 v[72:75], v[208:211], v[236:239], v[72:75]
	v_exp_f32_e32 v237, v124
	v_exp_f32_e32 v239, v125
	v_exp_f32_e32 v236, v116
	v_mfma_f32_16x16x32_bf16 v[140:143], v[248:251], v[140:143], v[244:247]
	v_exp_f32_e32 v238, v117
	ds_read_b128 v[120:123], v0 offset:26240
	v_mfma_f32_16x16x32_bf16 v[136:139], v[248:251], v[136:139], v[152:155]
	v_exp_f32_e32 v245, v126
	v_exp_f32_e32 v247, v127
	ds_read_b128 v[152:155], v0 offset:128
	s_waitcnt lgkmcnt(2)
	v_mfma_f32_16x16x32_bf16 v[92:95], v[148:151], v[128:131], v[92:95]
	ds_read_b128 v[124:127], v0 offset:21888
	v_exp_f32_e32 v244, v118
	v_mfma_f32_16x16x32_bf16 v[68:71], v[208:211], v[128:131], v[68:71]
	ds_read_b128 v[128:131], v0 offset:30592
	v_exp_f32_e32 v246, v119
	s_waitcnt lgkmcnt(2)
	v_mfma_f32_16x16x32_bf16 v[100:103], v[148:151], v[152:155], v[100:103]
	v_mfma_f32_16x16x32_bf16 v[80:83], v[208:211], v[152:155], v[80:83]
	ds_read_b128 v[152:155], v0 offset:4480
	s_waitcnt lgkmcnt(2)
	v_mfma_f32_16x16x32_bf16 v[88:91], v[148:151], v[124:127], v[88:91]
	v_mfma_f32_16x16x32_bf16 v[124:127], v[208:211], v[124:127], v[140:143]
	v_mfma_f32_16x16x32_bf16 v[104:107], v[148:151], v[120:123], v[104:107]
	s_nop 1
	v_cvt_pk_bf16_f32 v140, v170, v220
	v_cvt_pk_bf16_f32 v141, v240, v242
	v_cvt_pk_bf16_f32 v142, v236, v238
	v_mfma_f32_16x16x32_bf16 v[120:123], v[208:211], v[120:123], v[136:139]
	v_cvt_pk_bf16_f32 v143, v244, v246
	s_waitcnt lgkmcnt(1)
	v_mfma_f32_16x16x32_bf16 v[116:119], v[148:151], v[128:131], v[132:135]
	ds_read_b128 v[136:139], v0 offset:192
	s_nop 1
	v_cvt_pk_bf16_f32 v132, v171, v221
	v_cvt_pk_bf16_f32 v133, v241, v243
	v_cvt_pk_bf16_f32 v134, v237, v239
	v_cvt_pk_bf16_f32 v135, v245, v247
	s_waitcnt lgkmcnt(1)
	v_mfma_f32_16x16x32_bf16 v[96:99], v[148:151], v[152:155], v[96:99]
	v_mfma_f32_16x16x32_bf16 v[76:79], v[208:211], v[152:155], v[76:79]
	ds_read_b128 v[152:155], v0 offset:17536
	s_waitcnt lgkmcnt(1)
	v_mfma_f32_16x16x32_bf16 v[100:103], v[132:135], v[136:139], v[100:103]
	v_mfma_f32_16x16x32_bf16 v[80:83], v[140:143], v[136:139], v[80:83]
	ds_read_b128 v[136:139], v0 offset:4544
	v_mfma_f32_16x16x32_bf16 v[128:131], v[208:211], v[128:131], v[144:147]
	s_nop 2
	v_add_f32_e32 v144, 0, v198
	v_add_f32_e32 v145, 0, v199
	s_waitcnt lgkmcnt(1)
	v_mfma_f32_16x16x32_bf16 v[108:111], v[148:151], v[152:155], v[108:111]
	v_add_f32_e32 v148, v202, v144
	v_add_f32_e32 v149, v203, v145
	ds_read_b128 v[144:147], v0 offset:8896
	s_waitcnt lgkmcnt(1)
	v_mfma_f32_16x16x32_bf16 v[96:99], v[132:135], v[136:139], v[96:99]
	v_mfma_f32_16x16x32_bf16 v[76:79], v[140:143], v[136:139], v[76:79]
	v_add_f32_e32 v136, v194, v148
	v_add_f32_e32 v137, v195, v149
	v_add_f32_e32 v136, v196, v136
	v_add_f32_e32 v137, v197, v137
	s_waitcnt lgkmcnt(0)
	v_mfma_f32_16x16x32_bf16 v[112:115], v[132:135], v[144:147], v[112:115]
	v_add_f32_e32 v136, v200, v136
	v_add_f32_e32 v137, v201, v137
	v_add_f32_e32 v136, v176, v136
	v_add_f32_e32 v137, v177, v137
	v_mfma_f32_16x16x32_bf16 v[72:75], v[140:143], v[144:147], v[72:75]
	v_add_f32_e32 v148, v178, v136
	v_add_f32_e32 v149, v179, v137
	ds_read_b128 v[136:139], v0 offset:13248
	v_add_f32_e32 v144, v172, v148
	v_add_f32_e32 v145, v173, v149
	s_waitcnt lgkmcnt(0)
	v_mfma_f32_16x16x32_bf16 v[92:95], v[132:135], v[136:139], v[92:95]
	v_add_f32_e32 v144, v174, v144
	v_add_f32_e32 v145, v175, v145
	v_add_f32_e32 v144, v160, v144
	v_add_f32_e32 v145, v161, v145
	v_mfma_f32_16x16x32_bf16 v[68:71], v[140:143], v[136:139], v[68:71]
	v_add_f32_e32 v144, v164, v144
	v_add_f32_e32 v145, v165, v145
	v_add_f32_e32 v148, v162, v144
	v_add_f32_e32 v149, v163, v145
	ds_read_b128 v[144:147], v0 offset:17600
	v_add_f32_e32 v136, v166, v148
	v_add_f32_e32 v137, v167, v149
	v_mfma_f32_16x16x32_bf16 v[64:67], v[208:211], v[152:155], v[64:67]
	v_add_f32_e32 v136, v156, v136
	v_add_f32_e32 v137, v157, v137
	v_add_f32_e32 v136, v168, v136
	v_add_f32_e32 v137, v169, v137
	s_waitcnt lgkmcnt(0)
	v_mfma_f32_16x16x32_bf16 v[108:111], v[132:135], v[144:147], v[108:111]
	v_add_f32_e32 v136, v158, v136
	v_add_f32_e32 v137, v159, v137
	v_add_f32_e32 v52, v52, v136
	v_add_f32_e32 v53, v53, v137
	ds_read_b128 v[136:139], v0 offset:21952
	v_add_f32_e32 v52, v54, v52
	v_add_f32_e32 v53, v55, v53
	v_mfma_f32_16x16x32_bf16 v[64:67], v[140:143], v[144:147], v[64:67]
	v_add_f32_e32 v52, v56, v52
	v_add_f32_e32 v53, v57, v53
	v_add_f32_e32 v52, v62, v52
	v_add_f32_e32 v53, v63, v53
	s_waitcnt lgkmcnt(0)
	v_mfma_f32_16x16x32_bf16 v[88:91], v[132:135], v[136:139], v[88:91]
	v_add_f32_e32 v52, v58, v52
	v_add_f32_e32 v53, v59, v53
	v_add_f32_e32 v56, v60, v52
	v_add_f32_e32 v57, v61, v53
	ds_read_b128 v[52:55], v0 offset:26304
	v_add_f32_e32 v56, v84, v56
	v_add_f32_e32 v57, v85, v57
	v_mfma_f32_16x16x32_bf16 v[60:63], v[140:143], v[136:139], v[124:127]
	v_add_f32_e32 v56, v86, v56
	v_add_f32_e32 v57, v87, v57
	v_add_f32_e32 v56, v170, v56
	v_add_f32_e32 v57, v171, v57
	s_waitcnt lgkmcnt(0)
	v_mfma_f32_16x16x32_bf16 v[104:107], v[132:135], v[52:55], v[104:107]
	v_add_f32_e32 v56, v220, v56
	v_add_f32_e32 v57, v221, v57
	ds_read_b128 v[124:127], v0 offset:30656
	v_add_f32_e32 v84, v240, v56
	v_add_f32_e32 v85, v241, v57
	v_mfma_f32_16x16x32_bf16 v[56:59], v[140:143], v[52:55], v[120:123]
	v_add_f32_e32 v52, v242, v84
	v_add_f32_e32 v53, v243, v85
	v_add_f32_e32 v52, v236, v52
	v_add_f32_e32 v53, v237, v53
	s_waitcnt lgkmcnt(0)
	v_mfma_f32_16x16x32_bf16 v[84:87], v[132:135], v[124:127], v[116:119]
	v_add_f32_e32 v52, v238, v52
	v_add_f32_e32 v53, v239, v53
	v_add_f32_e32 v52, v244, v52
	v_add_f32_e32 v53, v245, v53
	s_nop 0
	v_add_f32_e32 v52, v246, v52
	v_add_f32_e32 v53, v247, v53
	s_nop 0
	v_fma_f32 v190, v190, v2, v52
	v_fma_f32 v191, v191, v3, v53
	v_mfma_f32_16x16x32_bf16 v[52:55], v[140:143], v[124:127], v[128:131]
	s_add_i32 s77, s77, 1
	s_cmp_eq_u32 s82, s77
	v_add_u32_e32 v234, 0x80, v234
	s_barrier
	s_cbranch_scc1 .LBB0_712
; #define MFMA(a, b, c) __builtin_amdgcn_mfma_f32_16x16x32_bf16(a, b, c, 0, 0, 0)
; DEV void attn_item(const Params& p, int layer, int h, int qb, float lam, bf16_t* lds) {
;     ...
;   for (int kb = 0; kb <= qb; kb++) {
;     const int cur = kb & 1;
;     const bf16_t* kp = KV + cur * TS + lr * PS + grp * 64 + lg * 8;
;     const bf16_t* vq = KV + 2 * TS + cur * TS + lr * PS + lg * 4;
;     {
;       bf16_t* sp = KV + (cur ^ 1) * TS + lrow * PS + lc8;
;       ASTORE(sp)
;     }
;     __builtin_amdgcn_sched_barrier(0);
;     f32x4 s[2][8];
;     {
; #pragma unroll
;       for (int j = 0; j < 8; j++) {
;         const bf16x8 kf0 = *(const bf16x8*)(kp + j * 16 * PS);
;         const bf16x8 kf1 = *(const bf16x8*)(kp + j * 16 * PS + 32);
;         s[0][j] = MFMA(kf0, a00, ((f32x4){0.f, 0.f, 0.f, 0.f}));
;         s[1][j] = MFMA(kf0, a10, ((f32x4){0.f, 0.f, 0.f, 0.f}));
;         s[0][j] = MFMA(kf1, a01, s[0][j]);
;         s[1][j] = MFMA(kf1, a11, s[1][j]);
;       }
;     }
;     __builtin_amdgcn_sched_barrier(0);
;     {
;       const int kbn = (kb + 2 <= qb) ? kb + 2 : qb;
;       ALOAD(kbn)
;     }
;     __builtin_amdgcn_sched_barrier(0);
;     if (kb == qb || kb == 0) {
.LBB0_708:
	s_and_b32 s0, s77, 1
	s_mul_i32 s67, s0, 0x4400
	s_xor_b32 s0, s0, 1
	s_mul_i32 s0, s0, 0x8800
	v_add_u32_e32 v2, s0, v230
	s_waitcnt vmcnt(7)
	ds_write_b128 v2, v[20:23]
	s_waitcnt vmcnt(6)
	ds_write_b128 v2, v[24:27] offset:8704
	s_waitcnt vmcnt(5)
	ds_write_b128 v2, v[28:31] offset:17408
	s_waitcnt vmcnt(4)
	ds_write_b128 v2, v[32:35] offset:26112
	v_add_u32_e32 v3, s0, v204
	v_add_u32_e32 v25, s0, v205
	s_nop 0
	s_waitcnt vmcnt(3)
	ds_write_b64 v3, v[36:37]
	ds_write_b64 v25, v[38:39]
	s_waitcnt vmcnt(2)
	ds_write_b64 v3, v[40:41] offset:8704
	ds_write_b64 v25, v[42:43] offset:8704
	v_lshl_add_u32 v0, s67, 1, v231
	s_waitcnt vmcnt(1)
	ds_write_b64 v3, v[44:45] offset:17408
	ds_write_b64 v25, v[46:47] offset:17408
	s_waitcnt vmcnt(0)
	ds_write_b64 v3, v[48:49] offset:26112
	ds_write_b64 v25, v[50:51] offset:26112
	v_cmp_neq_f32_e64 s[98:99], s68, v193
	v_cmp_neq_f32_e32 vcc, s68, v192
	s_nop 0
	v_cndmask_b32_e64 v206, 0, v193, s[98:99]
	v_cndmask_b32_e32 v212, 0, v192, vcc
	v_xor_b32_e32 v28, 0x80000000, v206
	v_xor_b32_e32 v48, 0x80000000, v212
	v_mov_b32_e32 v29, v28
	v_mov_b32_e32 v30, v28
	v_mov_b32_e32 v31, v28
	v_mov_b32_e32 v49, v48
	v_mov_b32_e32 v50, v48
	v_mov_b32_e32 v51, v48
	ds_read_b128 v[20:23], v0
	ds_read_b128 v[24:27], v0 offset:64
	ds_read_b128 v[32:35], v0 offset:4352
	ds_read_b128 v[36:39], v0 offset:4416
	ds_read_b128 v[40:43], v0 offset:8704
	ds_read_b128 v[44:47], v0 offset:8768
	s_waitcnt lgkmcnt(4)
	v_mfma_f32_16x16x32_bf16 v[176:179], v[20:23], v[4:7], v[28:31]
	v_mfma_f32_16x16x32_bf16 v[168:171], v[20:23], v[12:15], v[48:51]
	v_mfma_f32_16x16x32_bf16 v[176:179], v[24:27], v[8:11], v[176:179]
	v_mfma_f32_16x16x32_bf16 v[168:171], v[24:27], v[16:19], v[168:171]
	ds_read_b128 v[20:23], v0 offset:13056
	ds_read_b128 v[24:27], v0 offset:13120
	s_waitcnt lgkmcnt(4)
	v_mfma_f32_16x16x32_bf16 v[172:175], v[32:35], v[4:7], v[28:31]
	v_mfma_f32_16x16x32_bf16 v[164:167], v[32:35], v[12:15], v[48:51]
	v_mfma_f32_16x16x32_bf16 v[172:175], v[36:39], v[8:11], v[172:175]
	v_mfma_f32_16x16x32_bf16 v[164:167], v[36:39], v[16:19], v[164:167]
	ds_read_b128 v[32:35], v0 offset:17408
	ds_read_b128 v[36:39], v0 offset:17472
	s_waitcnt lgkmcnt(4)
	v_mfma_f32_16x16x32_bf16 v[160:163], v[40:43], v[4:7], v[28:31]
	v_mfma_f32_16x16x32_bf16 v[152:155], v[40:43], v[12:15], v[48:51]
	v_mfma_f32_16x16x32_bf16 v[160:163], v[44:47], v[8:11], v[160:163]
	v_mfma_f32_16x16x32_bf16 v[152:155], v[44:47], v[16:19], v[152:155]
	ds_read_b128 v[40:43], v0 offset:21760
	ds_read_b128 v[44:47], v0 offset:21824
	s_waitcnt lgkmcnt(4)
	v_mfma_f32_16x16x32_bf16 v[156:159], v[20:23], v[4:7], v[28:31]
	v_mfma_f32_16x16x32_bf16 v[148:151], v[20:23], v[12:15], v[48:51]
	v_mfma_f32_16x16x32_bf16 v[156:159], v[24:27], v[8:11], v[156:159]
	v_mfma_f32_16x16x32_bf16 v[148:151], v[24:27], v[16:19], v[148:151]
	ds_read_b128 v[20:23], v0 offset:26112
	ds_read_b128 v[24:27], v0 offset:26176
	s_waitcnt lgkmcnt(4)
	v_mfma_f32_16x16x32_bf16 v[144:147], v[32:35], v[4:7], v[28:31]
	v_mfma_f32_16x16x32_bf16 v[136:139], v[32:35], v[12:15], v[48:51]
	v_mfma_f32_16x16x32_bf16 v[144:147], v[36:39], v[8:11], v[144:147]
	v_mfma_f32_16x16x32_bf16 v[136:139], v[36:39], v[16:19], v[136:139]
	ds_read_b128 v[32:35], v0 offset:30464
	ds_read_b128 v[36:39], v0 offset:30528
	s_waitcnt lgkmcnt(4)
	v_mfma_f32_16x16x32_bf16 v[140:143], v[40:43], v[4:7], v[28:31]
	v_mfma_f32_16x16x32_bf16 v[132:135], v[40:43], v[12:15], v[48:51]
	v_mfma_f32_16x16x32_bf16 v[140:143], v[44:47], v[8:11], v[140:143]
	v_mfma_f32_16x16x32_bf16 v[132:135], v[44:47], v[16:19], v[132:135]
	s_waitcnt lgkmcnt(2)
	v_mfma_f32_16x16x32_bf16 v[128:131], v[20:23], v[4:7], v[28:31]
	v_mfma_f32_16x16x32_bf16 v[120:123], v[20:23], v[12:15], v[48:51]
	v_mfma_f32_16x16x32_bf16 v[128:131], v[24:27], v[8:11], v[128:131]
	v_mfma_f32_16x16x32_bf16 v[120:123], v[24:27], v[16:19], v[120:123]
	s_waitcnt lgkmcnt(0)
	v_mfma_f32_16x16x32_bf16 v[124:127], v[32:35], v[4:7], v[28:31]
	v_mfma_f32_16x16x32_bf16 v[116:119], v[32:35], v[12:15], v[48:51]
	v_mfma_f32_16x16x32_bf16 v[124:127], v[36:39], v[8:11], v[124:127]
	v_mfma_f32_16x16x32_bf16 v[116:119], v[36:39], v[16:19], v[116:119]
	s_nop 0
	s_add_i32 s0, s77, 2
	s_min_u32 s0, s0, s76
	v_lshl_add_u32 v0, s0, 17, v186
	s_nop 1
	v_lshlrev_b32_e32 v2, 1, v0
	v_lshl_add_u32 v0, s0, 7, v188
	v_add_u32_e32 v3, 0x10000, v2
	v_add_u32_e32 v28, 0x20000, v2
	v_add_u32_e32 v32, 0x30000, v2
	global_load_dwordx4 v[20:23], v2, s[78:79]
	global_load_dwordx4 v[24:27], v3, s[78:79]
	v_lshlrev_b32_e32 v2, 1, v0
	global_load_dwordx4 v[28:31], v28, s[78:79]
	global_load_dwordx4 v[32:35], v32, s[78:79]
	v_add_u32_e32 v3, 0x82000, v2
	v_add_u32_e32 v44, 0x104000, v2
	v_add_u32_e32 v48, 0x186000, v2
	global_load_dwordx4 v[36:39], v2, s[70:71]
	global_load_dwordx4 v[40:43], v3, s[70:71]
	global_load_dwordx4 v[44:47], v44, s[70:71]
	global_load_dwordx4 v[48:51], v48, s[70:71]
	s_cmp_lg_u32 s76, s77
	s_cselect_b64 s[0:1], -1, 0
	s_cmp_eq_u32 s77, 0
	s_cselect_b64 s[2:3], -1, 0
	s_cmp_lg_u32 s77, 0
	s_cselect_b64 s[6:7], -1, 0
	s_and_b64 s[0:1], s[0:1], s[6:7]
	s_and_b64 vcc, exec, s[0:1]
	s_cbranch_vccnz .LBB0_710
; DEV void attn_item(const Params& p, int layer, int h, int qb, float lam, bf16_t* lds) {
;     ...
;     if (kb == qb || kb == 0) {
; #pragma unroll
;       for (int i = 0; i < 2; i++)
; #pragma unroll
;         for (int j = 0; j < 8; j++)
; #pragma unroll
;           for (int r = 0; r < 4; r++) {
;             const int key = kb * 128 + j * 16 + lg * 4 + r;
;             if (key > qrow0 + 16 * i || key < 112) s[i][j][r] = -1e30f;
;           }
;     }
	v_cmp_gt_u32_e32 vcc, v234, v184
	v_mov_b32_e32 v0, s68
	s_or_b64 s[0:1], s[2:3], vcc
	v_cndmask_b32_e64 v176, v176, v0, s[0:1]
	v_cmp_ge_u32_e64 s[0:1], v234, v184
	s_or_b64 s[0:1], s[2:3], s[0:1]
	v_add_u32_e32 v2, 2, v234
	v_cndmask_b32_e64 v177, v177, v219, s[0:1]
	v_cmp_gt_u32_e64 s[0:1], v2, v184
	s_or_b64 s[0:1], s[2:3], s[0:1]
	v_add_u32_e32 v3, 3, v234
	v_cndmask_b32_e64 v178, v178, v219, s[0:1]
	v_cmp_gt_u32_e64 s[0:1], v3, v184
	s_or_b64 s[0:1], s[2:3], s[0:1]
	v_add_u32_e32 v0, 16, v234
	v_cndmask_b32_e64 v179, v179, v219, s[0:1]
	v_cmp_gt_u32_e64 s[0:1], v0, v184
	v_cmp_gt_u32_e64 s[6:7], s61, v0
	v_mov_b32_e32 v0, s68
	s_or_b64 s[0:1], s[0:1], s[6:7]
	v_add_u32_e32 v194, 17, v234
	v_cndmask_b32_e64 v172, v172, v0, s[0:1]
	v_cmp_gt_u32_e64 s[0:1], v194, v184
	v_cmp_gt_u32_e64 s[8:9], s61, v194
	s_or_b64 s[0:1], s[0:1], s[8:9]
	v_add_u32_e32 v195, 18, v234
	v_cndmask_b32_e64 v173, v173, v219, s[0:1]
	v_cmp_gt_u32_e64 s[0:1], v195, v184
	v_cmp_gt_u32_e64 s[10:11], s61, v195
	s_or_b64 s[0:1], s[0:1], s[10:11]
	v_add_u32_e32 v196, 19, v234
	v_cndmask_b32_e64 v174, v174, v219, s[0:1]
	v_cmp_gt_u32_e64 s[0:1], v196, v184
	v_cmp_gt_u32_e64 s[12:13], s61, v196
	s_or_b64 s[0:1], s[0:1], s[12:13]
	v_add_u32_e32 v197, 32, v234
	v_cndmask_b32_e64 v175, v175, v219, s[0:1]
	v_cmp_gt_u32_e64 s[0:1], v197, v184
	v_cmp_gt_u32_e64 s[14:15], s61, v197
	s_or_b64 s[0:1], s[0:1], s[14:15]
	v_add_u32_e32 v198, 33, v234
	s_or_b64 vcc, vcc, s[6:7]
	v_cndmask_b32_e64 v160, v160, v0, s[0:1]
	v_cmp_gt_u32_e64 s[0:1], v198, v184
	v_cmp_gt_u32_e64 s[16:17], s61, v198
	v_cndmask_b32_e32 v164, v164, v0, vcc
	v_cmp_gt_u32_e32 vcc, v194, v233
	s_or_b64 s[0:1], s[0:1], s[16:17]
	v_add_u32_e32 v199, 34, v234
	s_or_b64 vcc, vcc, s[8:9]
	v_cndmask_b32_e64 v161, v161, v219, s[0:1]
	v_cmp_gt_u32_e64 s[0:1], v199, v184
	v_cmp_gt_u32_e64 s[18:19], s61, v199
	v_cndmask_b32_e32 v165, v165, v219, vcc
	v_cmp_gt_u32_e32 vcc, v195, v233
	s_or_b64 s[0:1], s[0:1], s[18:19]
	v_add_u32_e32 v200, 35, v234
	s_or_b64 vcc, vcc, s[10:11]
	v_cndmask_b32_e64 v162, v162, v219, s[0:1]
	v_cmp_gt_u32_e64 s[0:1], v200, v184
	v_cmp_gt_u32_e64 s[20:21], s61, v200
	v_cndmask_b32_e32 v166, v166, v219, vcc
	v_cmp_gt_u32_e32 vcc, v196, v233
	s_or_b64 s[0:1], s[0:1], s[20:21]
	v_add_u32_e32 v201, 48, v234
	s_or_b64 vcc, vcc, s[12:13]
	v_cndmask_b32_e64 v163, v163, v219, s[0:1]
	v_cmp_gt_u32_e64 s[0:1], v201, v184
	v_cmp_gt_u32_e64 s[22:23], s61, v201
	v_cndmask_b32_e32 v167, v167, v219, vcc
	v_cmp_gt_u32_e32 vcc, v197, v233
	s_or_b64 s[0:1], s[0:1], s[22:23]
	v_add_u32_e32 v202, 49, v234
	s_or_b64 vcc, vcc, s[14:15]
	v_cndmask_b32_e64 v156, v156, v0, s[0:1]
	v_cmp_gt_u32_e64 s[0:1], v202, v184
	v_cmp_gt_u32_e64 s[24:25], s61, v202
	v_cndmask_b32_e32 v152, v152, v0, vcc
	v_cmp_gt_u32_e32 vcc, v198, v233
	s_or_b64 s[0:1], s[0:1], s[24:25]
	v_add_u32_e32 v203, 50, v234
	s_or_b64 vcc, vcc, s[16:17]
	v_cndmask_b32_e64 v157, v157, v219, s[0:1]
	v_cmp_gt_u32_e64 s[0:1], v203, v184
	v_cmp_gt_u32_e64 s[26:27], s61, v203
	v_cndmask_b32_e32 v153, v153, v219, vcc
	v_cmp_gt_u32_e32 vcc, v199, v233
	s_or_b64 s[0:1], s[0:1], s[26:27]
	v_add_u32_e32 v208, 51, v234
	s_or_b64 vcc, vcc, s[18:19]
	v_cndmask_b32_e64 v158, v158, v219, s[0:1]
	v_cmp_gt_u32_e64 s[0:1], v208, v184
	v_cmp_gt_u32_e64 s[28:29], s61, v208
	v_cndmask_b32_e32 v154, v154, v219, vcc
	v_cmp_gt_u32_e32 vcc, v200, v233
	s_or_b64 s[0:1], s[0:1], s[28:29]
	v_add_u32_e32 v209, 64, v234
	s_or_b64 vcc, vcc, s[20:21]
	v_cndmask_b32_e64 v159, v159, v219, s[0:1]
	v_cmp_gt_u32_e64 s[0:1], v209, v184
	v_cmp_gt_u32_e64 s[30:31], s61, v209
	v_cndmask_b32_e32 v155, v155, v219, vcc
	v_cmp_gt_u32_e32 vcc, v201, v233
	s_or_b64 s[0:1], s[0:1], s[30:31]
	v_add_u32_e32 v210, 0x41, v234
	s_or_b64 vcc, vcc, s[22:23]
	v_cndmask_b32_e64 v144, v144, v0, s[0:1]
	v_cmp_gt_u32_e64 s[0:1], v210, v184
	v_cmp_gt_u32_e64 s[34:35], s61, v210
	v_cndmask_b32_e32 v148, v148, v0, vcc
	v_cmp_gt_u32_e32 vcc, v202, v233
	s_or_b64 s[0:1], s[0:1], s[34:35]
	v_add_u32_e32 v211, 0x42, v234
	s_or_b64 vcc, vcc, s[24:25]
	v_cndmask_b32_e64 v145, v145, v219, s[0:1]
	v_cmp_gt_u32_e64 s[0:1], v211, v184
	v_cmp_gt_u32_e64 s[36:37], s61, v211
	v_cndmask_b32_e32 v149, v149, v219, vcc
	v_cmp_gt_u32_e32 vcc, v203, v233
	s_or_b64 s[0:1], s[0:1], s[36:37]
	v_add_u32_e32 v220, 0x43, v234
	s_or_b64 vcc, vcc, s[26:27]
	v_cndmask_b32_e64 v146, v146, v219, s[0:1]
; DEV void attn_item(const Params& p, int layer, int h, int qb, float lam, bf16_t* lds) {
;     ...
;     if (kb == qb || kb == 0) {
; #pragma unroll
;       for (int i = 0; i < 2; i++)
; #pragma unroll
;         for (int j = 0; j < 8; j++)
; #pragma unroll
;           for (int r = 0; r < 4; r++) {
;             const int key = kb * 128 + j * 16 + lg * 4 + r;
;             if (key > qrow0 + 16 * i || key < 112) s[i][j][r] = -1e30f;
;           }
;     }
	v_cmp_gt_u32_e64 s[0:1], v220, v184
	v_cmp_gt_u32_e64 s[38:39], s61, v220
	v_cndmask_b32_e32 v150, v150, v219, vcc
	v_cmp_gt_u32_e32 vcc, v208, v233
	s_or_b64 s[0:1], s[0:1], s[38:39]
	v_add_u32_e32 v221, 0x50, v234
	s_or_b64 vcc, vcc, s[28:29]
	v_cndmask_b32_e64 v147, v147, v219, s[0:1]
	v_cmp_gt_u32_e64 s[0:1], v221, v184
	v_cmp_gt_u32_e64 s[40:41], s61, v221
	v_cndmask_b32_e32 v151, v151, v219, vcc
	v_cmp_gt_u32_e32 vcc, v209, v233
	s_or_b64 s[0:1], s[0:1], s[40:41]
	v_add_u32_e32 v236, 0x51, v234
	s_or_b64 vcc, vcc, s[30:31]
	v_cndmask_b32_e64 v140, v140, v0, s[0:1]
	v_cmp_gt_u32_e64 s[0:1], v236, v184
	v_cmp_gt_u32_e64 s[42:43], s61, v236
	v_cndmask_b32_e32 v136, v136, v0, vcc
	v_cmp_gt_u32_e32 vcc, v210, v233
	s_or_b64 s[0:1], s[0:1], s[42:43]
	v_add_u32_e32 v237, 0x52, v234
	s_or_b64 vcc, vcc, s[34:35]
	v_cndmask_b32_e64 v141, v141, v219, s[0:1]
	v_cmp_gt_u32_e64 s[0:1], v237, v184
	v_cmp_gt_u32_e64 s[44:45], s61, v237
	v_cndmask_b32_e32 v137, v137, v219, vcc
	v_cmp_gt_u32_e32 vcc, v211, v233
	s_or_b64 s[0:1], s[0:1], s[44:45]
	v_add_u32_e32 v238, 0x53, v234
	s_or_b64 vcc, vcc, s[36:37]
	v_cndmask_b32_e64 v142, v142, v219, s[0:1]
	v_cmp_gt_u32_e64 s[0:1], v238, v184
	v_cmp_gt_u32_e64 s[46:47], s61, v238
	v_cndmask_b32_e32 v138, v138, v219, vcc
	v_cmp_gt_u32_e32 vcc, v220, v233
	s_or_b64 s[0:1], s[0:1], s[46:47]
	v_add_u32_e32 v239, 0x60, v234
	s_or_b64 vcc, vcc, s[38:39]
	v_cndmask_b32_e64 v143, v143, v219, s[0:1]
	v_cmp_gt_u32_e64 s[0:1], v239, v184
	v_cmp_gt_u32_e64 s[48:49], s61, v239
	v_cndmask_b32_e32 v139, v139, v219, vcc
	v_cmp_gt_u32_e32 vcc, v221, v233
	s_or_b64 s[0:1], s[0:1], s[48:49]
	v_add_u32_e32 v240, 0x61, v234
	s_or_b64 vcc, vcc, s[40:41]
	v_cndmask_b32_e64 v128, v128, v0, s[0:1]
	v_cmp_gt_u32_e64 s[52:53], v240, v184
	v_cmp_gt_u32_e64 s[0:1], s61, v240
	v_cndmask_b32_e32 v132, v132, v0, vcc
	v_cmp_gt_u32_e32 vcc, v236, v233
	s_or_b64 s[52:53], s[52:53], s[0:1]
	v_add_u32_e32 v241, 0x62, v234
	s_or_b64 vcc, vcc, s[42:43]
	v_cndmask_b32_e64 v129, v129, v219, s[52:53]
	v_cmp_gt_u32_e64 s[54:55], v241, v184
	v_cmp_gt_u32_e64 s[52:53], s61, v241
	v_cndmask_b32_e32 v133, v133, v219, vcc
	v_cmp_gt_u32_e32 vcc, v237, v233
	s_or_b64 s[54:55], s[54:55], s[52:53]
	v_add_u32_e32 v242, 0x63, v234
	s_or_b64 vcc, vcc, s[44:45]
	v_cndmask_b32_e64 v130, v130, v219, s[54:55]
	v_cmp_gt_u32_e64 s[58:59], v242, v184
	v_cmp_gt_u32_e64 s[54:55], s61, v242
	v_cndmask_b32_e32 v134, v134, v219, vcc
	v_cmp_gt_u32_e32 vcc, v238, v233
	s_or_b64 s[58:59], s[58:59], s[54:55]
	v_add_u32_e32 v243, 0x70, v234
	s_or_b64 vcc, vcc, s[46:47]
	v_cndmask_b32_e64 v131, v131, v219, s[58:59]
	v_cmp_gt_u32_e64 s[58:59], v243, v184
	v_add_u32_e32 v244, 0x71, v234
	v_cndmask_b32_e32 v135, v135, v219, vcc
	v_cmp_gt_u32_e32 vcc, v239, v233
	v_cndmask_b32_e64 v124, v124, v0, s[58:59]
	v_cmp_le_u32_e64 s[58:59], v244, v184
	v_add_u32_e32 v245, 0x72, v234
	s_or_b64 vcc, vcc, s[48:49]
	v_cndmask_b32_e64 v125, v219, v125, s[58:59]
	v_cmp_le_u32_e64 s[58:59], v245, v184
	v_add_u32_e32 v246, 0x73, v234
	v_cndmask_b32_e32 v120, v120, v0, vcc
	v_cmp_gt_u32_e32 vcc, v240, v233
	v_cndmask_b32_e64 v126, v219, v126, s[58:59]
	v_cmp_le_u32_e64 s[58:59], v246, v184
	s_or_b64 vcc, vcc, s[0:1]
	v_cndmask_b32_e32 v121, v121, v219, vcc
	v_cndmask_b32_e64 v127, v219, v127, s[58:59]
	v_cmp_gt_u32_e64 s[58:59], v234, v233
	v_cmp_gt_u32_e32 vcc, v241, v233
	s_or_b64 s[58:59], s[2:3], s[58:59]
	s_or_b64 vcc, vcc, s[52:53]
	v_cndmask_b32_e64 v168, v168, v0, s[58:59]
	v_cmp_ge_u32_e64 s[58:59], v234, v233
	v_cndmask_b32_e32 v122, v122, v219, vcc
	v_cmp_gt_u32_e32 vcc, v242, v233
	s_or_b64 s[58:59], s[2:3], s[58:59]
	s_or_b64 vcc, vcc, s[54:55]
	v_cndmask_b32_e64 v169, v169, v219, s[58:59]
	v_cmp_gt_u32_e64 s[58:59], v2, v233
	v_cndmask_b32_e32 v123, v123, v219, vcc
	v_cmp_gt_u32_e32 vcc, v243, v233
	s_or_b64 s[58:59], s[2:3], s[58:59]
	v_cndmask_b32_e64 v170, v170, v219, s[58:59]
	v_cndmask_b32_e32 v116, v116, v0, vcc
	v_cmp_le_u32_e32 vcc, v244, v233
	v_cmp_gt_u32_e64 s[58:59], v3, v233
	s_or_b64 s[58:59], s[2:3], s[58:59]
	v_cndmask_b32_e32 v117, v219, v117, vcc
	v_cmp_le_u32_e32 vcc, v245, v233
	v_cndmask_b32_e64 v171, v171, v219, s[58:59]
	s_movk_i32 s31, 0x207f
	v_cndmask_b32_e32 v118, v219, v118, vcc
	v_cmp_le_u32_e32 vcc, v246, v233
	s_mov_b32 s30, 0x800000
	s_mov_b32 s39, s74
	v_cndmask_b32_e32 v119, v219, v119, vcc

; DEV float shfl_l(float v, int srclane) { return __int_as_float(__builtin_amdgcn_ds_bpermute(srclane << 2, __float_as_int(v))); }
; DEV void attn_item(const Params& p, int layer, int h, int qb, float lam, bf16_t* lds) {
;     ...
;     if (__builtin_amdgcn_ballot_w64(al[0] != 1.f || al[1] != 1.f) != 0ull) {
; #pragma unroll
;       for (int i = 0; i < 2; i++) {
;         float ao[4];
; #pragma unroll
;         for (int r = 0; r < 4; r++) ao[r] = shfl_l(al[i], lg * 4 + r);
; #pragma unroll
;         for (int je = 0; je < 8; je++)
; #pragma unroll
;           for (int r = 0; r < 4; r++) o[i][je][r] *= ao[r];
;       }
;     }
.Lattc_nofix:
	v_cmp_neq_f32_e32 vcc, 1.0, v3
	v_cmp_neq_f32_e64 s[0:1], 1.0, v2
	s_or_b64 vcc, s[0:1], vcc
	s_cbranch_vccz .LBB0_707
	ds_bpermute_b32 v194, v182, v3
	ds_bpermute_b32 v195, v227, v3
	ds_bpermute_b32 v196, v189, v3
	ds_bpermute_b32 v197, v187, v3
	s_waitcnt lgkmcnt(2)
	v_pk_mul_f32 v[100:101], v[100:101], v[194:195]
	v_pk_mul_f32 v[96:97], v[96:97], v[194:195]
	s_waitcnt lgkmcnt(0)
	v_pk_mul_f32 v[102:103], v[102:103], v[196:197]
	v_pk_mul_f32 v[98:99], v[98:99], v[196:197]
	v_pk_mul_f32 v[114:115], v[114:115], v[196:197]
	v_pk_mul_f32 v[112:113], v[112:113], v[194:195]
	v_pk_mul_f32 v[94:95], v[94:95], v[196:197]
	v_pk_mul_f32 v[92:93], v[92:93], v[194:195]
	v_pk_mul_f32 v[110:111], v[110:111], v[196:197]
	v_pk_mul_f32 v[108:109], v[108:109], v[194:195]
	v_pk_mul_f32 v[90:91], v[90:91], v[196:197]
	v_pk_mul_f32 v[88:89], v[88:89], v[194:195]
	v_pk_mul_f32 v[106:107], v[106:107], v[196:197]
	v_pk_mul_f32 v[104:105], v[104:105], v[194:195]
	v_pk_mul_f32 v[86:87], v[86:87], v[196:197]
	v_pk_mul_f32 v[84:85], v[84:85], v[194:195]
	ds_bpermute_b32 v194, v182, v2
	ds_bpermute_b32 v195, v227, v2
	ds_bpermute_b32 v196, v189, v2
	ds_bpermute_b32 v197, v187, v2
	s_waitcnt lgkmcnt(2)
	v_pk_mul_f32 v[80:81], v[80:81], v[194:195]
	v_pk_mul_f32 v[76:77], v[76:77], v[194:195]
	s_waitcnt lgkmcnt(0)
	v_pk_mul_f32 v[82:83], v[82:83], v[196:197]
	v_pk_mul_f32 v[78:79], v[78:79], v[196:197]
	v_pk_mul_f32 v[74:75], v[74:75], v[196:197]
	v_pk_mul_f32 v[72:73], v[72:73], v[194:195]
	v_pk_mul_f32 v[70:71], v[70:71], v[196:197]
	v_pk_mul_f32 v[68:69], v[68:69], v[194:195]
	v_pk_mul_f32 v[66:67], v[66:67], v[196:197]
	v_pk_mul_f32 v[64:65], v[64:65], v[194:195]
	v_pk_mul_f32 v[62:63], v[62:63], v[196:197]
	v_pk_mul_f32 v[60:61], v[60:61], v[194:195]
	v_pk_mul_f32 v[58:59], v[58:59], v[196:197]
	v_pk_mul_f32 v[56:57], v[56:57], v[194:195]
	v_pk_mul_f32 v[54:55], v[54:55], v[196:197]
	v_pk_mul_f32 v[52:53], v[52:53], v[194:195]
	s_branch .LBB0_707
	s_nop 0
